# attention prologue: third K tile DMA issued with the first three (before moba_select); masked units reuse moba_select's q rows instead of reloading them
# speedup vs baseline: 1.0026x; 1.0005x over previous
; __device__ __forceinline__ unsigned moba_select(int b, int h, int qb, const f16_t* Q, const float* __restrict__ kms) {
;     int tid_ = threadIdx.x; asm volatile("" : "+v"(tid_));
;     const int tid = tid_, lane = tid & 63, r32 = lane & 31, hi = lane >> 5; const int wid = __builtin_amdgcn_readfirstlane(tid >> 6);
;     const f16_t* Qw = Q + ((long)b * SEQ + qb * QB + wid * QBLK) * QP + h * HD;
;     f16x8 qr[4];
; #pragma unroll
;     for (int d0 = 0; d0 < 4; ++d0) qr[d0] = *reinterpret_cast<const f16x8*>(&Qw[(long)r32 * QP + d0 * 16 + hi * 8]);
;     float gsc[7];
; #pragma unroll
;     for (int j = 0; j < 7; ++j) {
; template <int THRL> __device__ __forceinline__ void attn_unit(int b, int h, int qb, const f16_t* Q, const f16_t* __restrict__ K, const f16_t* __restrict__ V, f16_t* O, const float* __restrict__ kms, char* shm) {
;     ...
;     const f16_t* ksrc = Kh + (long)lane * KP + wid * 8;
;     const f16_t* vsrc = Vh + (long)(16 * (wid & 3) + (lane >> 2)) * KP + (wid >> 2) * 32 + (lane & 3) * 8;
;     const unsigned kdst = lds0 + LDS_K + wid * 1024, vdst = lds0 + LDS_V + wid * 1024;
;     ...
;     const int vb0 = (int)(lds0 + LDS_V) + ((lane >> 4) & 1) * 32 + (lane & 3) * 8 + (4 * hi + ((lane & 15) >> 2)) * 64;
;     const char* Kbase = shm + LDS_K; f16x8 kf[8];
;     const lds_cptr shm3 = (lds_cptr)shm; const lds_cptr kp0 = shm3 + LDS_K + hi * 1024 + r32 * 16; const lds_cptr vp0 = shm3 + LDS_V + ((lane >> 4) & 1) * 32 + (lane & 3) * 8 + (4 * hi + ((lane & 15) >> 2)) * 64;
;     const int NT = (q0 + QB) / KVBLK;
;     DMA_K(0, 0); DMA_V(0, 0); DMA_K(1, SLOTB);
;     ...
;     const bool maskon = (qb > 3) && (O == Q);
;     ...
;     const bool maskon = qb > 3;
;     ...
;     unsigned selmask = 0xFFFFFFFFu;
;     SBAR();
;     if (maskon) selmask = moba_select(b, h, qb, Q, kms);
;     asm volatile("" : "+v"(selmask) :: "memory"); SBAR();
;     f16x8 qr[4];
; #pragma unroll
;     for (int d0 = 0; d0 < 4; ++d0) qr[d0] = *reinterpret_cast<const f16x8*>(&Qw[(long)r32 * QP + d0 * 16 + hi * 8]);
;     float mhat = 0.f, l_reg = 0.f; float z_; asm volatile("v_mov_b32 %0, 0" : "=v"(z_)); f32x16 o[2]; f32x16 negm;
;     ...
;     _Pragma("unroll") for (int r = 0; r < 16; ++r) { o[0][r] = z_; o[1][r] = z_; negm[r] = KEEP(0) ? z_ : -INFINITY; } asm volatile("" : "+v"(negm));
;     ...
;     bool resc = false;
;     ...
;     f32x16 pA0, pA1, pB0, pB1;
;     int sl_prev = 0, sl_cur = 0, sl_next = SLOTB;
;     ...
;     DMA_K(2, 2 * SLOTB);
.LBB0_530:
	v_mov_b32_e32 v150, v0
	s_and_b64 s[0:1], s[2:3], exec
	s_cselect_b32 s70, s7, s78
	v_readfirstlane_b32 s24, v150
	v_and_b32_e32 v201, 63, v150
	s_ashr_i32 s29, s24, 6
	v_lshlrev_b32_e32 v190, 10, v201
	s_lshl_b32 s0, s29, 3
	v_lshl_add_u64 v[2:3], s[58:59], 0, v[190:191]
	s_ashr_i32 s1, s0, 31
	v_lshl_add_u64 v[182:183], s[0:1], 1, v[2:3]
	s_lshl_b32 s0, s29, 4
	v_bfe_u32 v2, v150, 2, 4
	v_and_or_b32 v2, s0, 48, v2
	s_ashr_i32 s0, s24, 3
	s_lshl_b32 s71, s70, 8
	s_andn2_b32 s0, s0, 31
	s_or_b32 s8, s56, s71
	v_lshlrev_b32_e32 v190, 10, v2
	s_ashr_i32 s1, s0, 31
	s_lshl_b32 s11, s29, 10
	v_lshl_add_u64 v[2:3], s[60:61], 0, v[190:191]
	v_lshlrev_b32_e32 v202, 3, v150
	s_cmp_lg_u32 0, -1
	v_lshl_add_u64 v[2:3], s[0:1], 1, v[2:3]
	v_and_b32_e32 v203, 24, v202
	s_cselect_b32 s0, 0, 0
	v_lshlrev_b32_e32 v190, 1, v203
	s_add_i32 s76, s11, s0
	s_mov_b32 s0, m0
	s_mov_b32 m0, s76
	s_nop 0
	global_load_lds_dwordx4 v[182:183], off
	s_mov_b32 m0, s0
	v_lshl_add_u64 v[104:105], v[2:3], 0, v[190:191]
	s_add_i32 s77, s76, 0x6000
	s_mov_b32 s0, m0
	s_mov_b32 m0, s77
	s_nop 0
	global_load_lds_dwordx4 v[104:105], off
	s_mov_b32 m0, s0
	v_lshl_add_u64 v[2:3], v[182:183], 0, s[42:43]
	s_add_i32 s0, s76, 0x2000
	s_mov_b32 s1, m0
	s_mov_b32 m0, s0
	s_nop 0
	global_load_lds_dwordx4 v[2:3], off
	s_mov_b32 m0, s1
	v_lshl_add_u64 v[4:5], v[182:183], 0, s[44:45]
	s_add_i32 s0, s76, 0x4000
	s_mov_b32 s1, m0
	s_mov_b32 m0, s0
	s_nop 0
	global_load_lds_dwordx4 v[4:5], off
	s_mov_b32 m0, s1
	s_cmp_gt_u32 s70, 3
	s_cselect_b64 s[4:5], -1, 0
	s_cmp_lt_u32 s70, 4
	v_mov_b32_e32 v210, -1
	s_cbranch_scc1 .LBB0_538
	s_lshl_b32 s9, s29, 11
	s_add_u32 s36, s62, s64
	s_addc_u32 s37, s63, s65
	s_add_u32 s36, s36, s9
	s_addc_u32 s37, s37, 0
	v_lshlrev_b32_e32 v19, 2, v201
	global_load_dword v18, v19, s[36:37]
	s_lshl_b32 s0, s29, 5
	s_add_u32 s0, s8, s0
	s_addc_u32 s1, s57, 0
	s_lshl_b64 s[0:1], s[0:1], 11
	s_add_u32 s0, s79, s0
	s_addc_u32 s1, s14, s1
	v_and_b32_e32 v21, 31, v201
	v_lshrrev_b32_e32 v20, 5, v201
	v_lshlrev_b32_e32 v21, 11, v21
	v_lshl_or_b32 v21, v20, 4, v21
	global_load_dwordx4 v[2:5], v21, s[0:1]
	global_load_dwordx4 v[6:9], v21, s[0:1] offset:32
	global_load_dwordx4 v[10:13], v21, s[0:1] offset:64
	global_load_dwordx4 v[14:17], v21, s[0:1] offset:96
	s_mov_b32 s9, 0x15000
	s_lshl_b32 s30, s29, 8
	s_add_i32 s30, s30, s9
	v_add_u32_e32 v101, s30, v19
	v_lshl_add_u32 v100, v20, 5, s9
	s_waitcnt vmcnt(4)
	ds_write_b32 v101, v18
	s_waitcnt lgkmcnt(0)
	s_barrier
	ds_read_b128 v[54:57], v100 offset:0
	ds_read_b128 v[58:61], v100 offset:16
	ds_read_b128 v[62:65], v100 offset:64
	ds_read_b128 v[66:69], v100 offset:80
	ds_read_b128 v[70:73], v100 offset:128
	ds_read_b128 v[74:77], v100 offset:144
	ds_read_b128 v[78:81], v100 offset:192
	ds_read_b128 v[82:85], v100 offset:208
	ds_read_b128 v[106:109], v100 offset:256
	ds_read_b128 v[110:113], v100 offset:272
	ds_read_b128 v[114:117], v100 offset:320
	ds_read_b128 v[118:121], v100 offset:336
	ds_read_b128 v[122:125], v100 offset:384
	ds_read_b128 v[126:129], v100 offset:400
	ds_read_b128 v[130:133], v100 offset:448
	ds_read_b128 v[134:137], v100 offset:464
	s_waitcnt vmcnt(0)
	v_cvt_f32_f16_e32 v22, v2
	v_cvt_f32_f16_sdwa v23, v2 dst_sel:DWORD dst_unused:UNUSED_PAD src0_sel:WORD_1
	v_cvt_f32_f16_e32 v24, v3
	v_cvt_f32_f16_sdwa v25, v3 dst_sel:DWORD dst_unused:UNUSED_PAD src0_sel:WORD_1
	v_cvt_f32_f16_e32 v26, v4
	v_cvt_f32_f16_sdwa v27, v4 dst_sel:DWORD dst_unused:UNUSED_PAD src0_sel:WORD_1
	v_cvt_f32_f16_e32 v28, v5
	v_cvt_f32_f16_sdwa v29, v5 dst_sel:DWORD dst_unused:UNUSED_PAD src0_sel:WORD_1
	v_cvt_f32_f16_e32 v30, v6
	v_cvt_f32_f16_sdwa v31, v6 dst_sel:DWORD dst_unused:UNUSED_PAD src0_sel:WORD_1
	v_cvt_f32_f16_e32 v32, v7
	v_cvt_f32_f16_sdwa v33, v7 dst_sel:DWORD dst_unused:UNUSED_PAD src0_sel:WORD_1
	v_cvt_f32_f16_e32 v34, v8
	v_cvt_f32_f16_sdwa v35, v8 dst_sel:DWORD dst_unused:UNUSED_PAD src0_sel:WORD_1
	v_cvt_f32_f16_e32 v36, v9
	v_cvt_f32_f16_sdwa v37, v9 dst_sel:DWORD dst_unused:UNUSED_PAD src0_sel:WORD_1
	v_cvt_f32_f16_e32 v38, v10
	v_cvt_f32_f16_sdwa v39, v10 dst_sel:DWORD dst_unused:UNUSED_PAD src0_sel:WORD_1
	v_cvt_f32_f16_e32 v40, v11
	v_cvt_f32_f16_sdwa v41, v11 dst_sel:DWORD dst_unused:UNUSED_PAD src0_sel:WORD_1
	v_cvt_f32_f16_e32 v42, v12
	v_cvt_f32_f16_sdwa v43, v12 dst_sel:DWORD dst_unused:UNUSED_PAD src0_sel:WORD_1
	v_cvt_f32_f16_e32 v44, v13
	v_cvt_f32_f16_sdwa v45, v13 dst_sel:DWORD dst_unused:UNUSED_PAD src0_sel:WORD_1
	v_cvt_f32_f16_e32 v46, v14
	v_cvt_f32_f16_sdwa v47, v14 dst_sel:DWORD dst_unused:UNUSED_PAD src0_sel:WORD_1
	v_cvt_f32_f16_e32 v48, v15
	v_cvt_f32_f16_sdwa v49, v15 dst_sel:DWORD dst_unused:UNUSED_PAD src0_sel:WORD_1
	v_cvt_f32_f16_e32 v50, v16
	v_cvt_f32_f16_sdwa v51, v16 dst_sel:DWORD dst_unused:UNUSED_PAD src0_sel:WORD_1
	v_cvt_f32_f16_e32 v52, v17
	v_cvt_f32_f16_sdwa v53, v17 dst_sel:DWORD dst_unused:UNUSED_PAD src0_sel:WORD_1
	s_waitcnt lgkmcnt(8)
	v_pk_mul_f32 v[86:87], v[22:23], v[54:55]
	v_pk_mul_f32 v[88:89], v[24:25], v[56:57]
	v_pk_fma_f32 v[86:87], v[26:27], v[58:59], v[86:87]
	v_pk_fma_f32 v[88:89], v[28:29], v[60:61], v[88:89]
	v_pk_fma_f32 v[86:87], v[30:31], v[62:63], v[86:87]
	v_pk_fma_f32 v[88:89], v[32:33], v[64:65], v[88:89]
	v_pk_fma_f32 v[86:87], v[34:35], v[66:67], v[86:87]
	v_pk_fma_f32 v[88:89], v[36:37], v[68:69], v[88:89]
	v_pk_fma_f32 v[86:87], v[38:39], v[70:71], v[86:87]
	v_pk_fma_f32 v[88:89], v[40:41], v[72:73], v[88:89]
	v_pk_fma_f32 v[86:87], v[42:43], v[74:75], v[86:87]
	v_pk_fma_f32 v[88:89], v[44:45], v[76:77], v[88:89]
	v_pk_fma_f32 v[86:87], v[46:47], v[78:79], v[86:87]
	v_pk_fma_f32 v[88:89], v[48:49], v[80:81], v[88:89]
	v_pk_fma_f32 v[86:87], v[50:51], v[82:83], v[86:87]
	v_pk_fma_f32 v[88:89], v[52:53], v[84:85], v[88:89]
	ds_read_b128 v[54:57], v100 offset:512
	ds_read_b128 v[58:61], v100 offset:528
	ds_read_b128 v[62:65], v100 offset:576
	ds_read_b128 v[66:69], v100 offset:592
	ds_read_b128 v[70:73], v100 offset:640
	ds_read_b128 v[74:77], v100 offset:656
	ds_read_b128 v[78:81], v100 offset:704
	ds_read_b128 v[82:85], v100 offset:720
	v_pk_add_f32 v[86:87], v[86:87], v[88:89]
	s_nop 0
	v_add_f32_e32 v138, v86, v87
	s_waitcnt lgkmcnt(8)
; __device__ __forceinline__ unsigned moba_select(int b, int h, int qb, const f16_t* Q, const float* __restrict__ kms) {
;     ...
;     for (int j = 0; j < 7; ++j) {
;         float s = 0.f;
;         if (j < qb) {
;             const float* km = kms + (size_t)(b * NBLK + j) * AW + h * HD + hi * 8;
; #pragma unroll
;             for (int d0 = 0; d0 < 4; ++d0) {
;                 const f32x4 k0 = *(const f32x4*)(km + d0 * 16), k1 = *(const f32x4*)(km + d0 * 16 + 4);
;                 s += (float)qr[d0][0] * k0[0] + (float)qr[d0][1] * k0[1] + (float)qr[d0][2] * k0[2] + (float)qr[d0][3] * k0[3];
;                 s += (float)qr[d0][4] * k1[0] + (float)qr[d0][5] * k1[1] + (float)qr[d0][6] * k1[2] + (float)qr[d0][7] * k1[3];
;             }
;             s += __shfl_xor(s, 32);
	v_pk_mul_f32 v[90:91], v[22:23], v[106:107]
	v_pk_mul_f32 v[92:93], v[24:25], v[108:109]
	v_pk_fma_f32 v[90:91], v[26:27], v[110:111], v[90:91]
	v_pk_fma_f32 v[92:93], v[28:29], v[112:113], v[92:93]
	v_pk_fma_f32 v[90:91], v[30:31], v[114:115], v[90:91]
	v_pk_fma_f32 v[92:93], v[32:33], v[116:117], v[92:93]
	v_pk_fma_f32 v[90:91], v[34:35], v[118:119], v[90:91]
	v_pk_fma_f32 v[92:93], v[36:37], v[120:121], v[92:93]
	v_pk_fma_f32 v[90:91], v[38:39], v[122:123], v[90:91]
	v_pk_fma_f32 v[92:93], v[40:41], v[124:125], v[92:93]
	v_pk_fma_f32 v[90:91], v[42:43], v[126:127], v[90:91]
	v_pk_fma_f32 v[92:93], v[44:45], v[128:129], v[92:93]
	v_pk_fma_f32 v[90:91], v[46:47], v[130:131], v[90:91]
	v_pk_fma_f32 v[92:93], v[48:49], v[132:133], v[92:93]
	v_pk_fma_f32 v[90:91], v[50:51], v[134:135], v[90:91]
	v_pk_fma_f32 v[92:93], v[52:53], v[136:137], v[92:93]
	ds_read_b128 v[106:109], v100 offset:768
	ds_read_b128 v[110:113], v100 offset:784
	ds_read_b128 v[114:117], v100 offset:832
	ds_read_b128 v[118:121], v100 offset:848
	ds_read_b128 v[122:125], v100 offset:896
	ds_read_b128 v[126:129], v100 offset:912
	ds_read_b128 v[130:133], v100 offset:960
	ds_read_b128 v[134:137], v100 offset:976
	v_pk_add_f32 v[90:91], v[90:91], v[92:93]
	s_nop 0
	v_add_f32_e32 v139, v90, v91
	s_waitcnt lgkmcnt(8)
	v_pk_mul_f32 v[86:87], v[22:23], v[54:55]
	v_pk_mul_f32 v[88:89], v[24:25], v[56:57]
	v_pk_fma_f32 v[86:87], v[26:27], v[58:59], v[86:87]
	v_pk_fma_f32 v[88:89], v[28:29], v[60:61], v[88:89]
	v_pk_fma_f32 v[86:87], v[30:31], v[62:63], v[86:87]
	v_pk_fma_f32 v[88:89], v[32:33], v[64:65], v[88:89]
	v_pk_fma_f32 v[86:87], v[34:35], v[66:67], v[86:87]
	v_pk_fma_f32 v[88:89], v[36:37], v[68:69], v[88:89]
	v_pk_fma_f32 v[86:87], v[38:39], v[70:71], v[86:87]
	v_pk_fma_f32 v[88:89], v[40:41], v[72:73], v[88:89]
	v_pk_fma_f32 v[86:87], v[42:43], v[74:75], v[86:87]
	v_pk_fma_f32 v[88:89], v[44:45], v[76:77], v[88:89]
	v_pk_fma_f32 v[86:87], v[46:47], v[78:79], v[86:87]
	v_pk_fma_f32 v[88:89], v[48:49], v[80:81], v[88:89]
	v_pk_fma_f32 v[86:87], v[50:51], v[82:83], v[86:87]
	v_pk_fma_f32 v[88:89], v[52:53], v[84:85], v[88:89]
	ds_read_b128 v[54:57], v100 offset:1024
	ds_read_b128 v[58:61], v100 offset:1040
	ds_read_b128 v[62:65], v100 offset:1088
	ds_read_b128 v[66:69], v100 offset:1104
	ds_read_b128 v[70:73], v100 offset:1152
	ds_read_b128 v[74:77], v100 offset:1168
	ds_read_b128 v[78:81], v100 offset:1216
	ds_read_b128 v[82:85], v100 offset:1232
	v_pk_add_f32 v[86:87], v[86:87], v[88:89]
	s_nop 0
	v_add_f32_e32 v140, v86, v87
	s_waitcnt lgkmcnt(8)
	v_pk_mul_f32 v[90:91], v[22:23], v[106:107]
	v_pk_mul_f32 v[92:93], v[24:25], v[108:109]
	v_pk_fma_f32 v[90:91], v[26:27], v[110:111], v[90:91]
	v_pk_fma_f32 v[92:93], v[28:29], v[112:113], v[92:93]
	v_pk_fma_f32 v[90:91], v[30:31], v[114:115], v[90:91]
	v_pk_fma_f32 v[92:93], v[32:33], v[116:117], v[92:93]
	v_pk_fma_f32 v[90:91], v[34:35], v[118:119], v[90:91]
	v_pk_fma_f32 v[92:93], v[36:37], v[120:121], v[92:93]
	v_pk_fma_f32 v[90:91], v[38:39], v[122:123], v[90:91]
	v_pk_fma_f32 v[92:93], v[40:41], v[124:125], v[92:93]
	v_pk_fma_f32 v[90:91], v[42:43], v[126:127], v[90:91]
	v_pk_fma_f32 v[92:93], v[44:45], v[128:129], v[92:93]
	v_pk_fma_f32 v[90:91], v[46:47], v[130:131], v[90:91]
	v_pk_fma_f32 v[92:93], v[48:49], v[132:133], v[92:93]
	v_pk_fma_f32 v[90:91], v[50:51], v[134:135], v[90:91]
	v_pk_fma_f32 v[92:93], v[52:53], v[136:137], v[92:93]
	ds_read_b128 v[106:109], v100 offset:1280
	ds_read_b128 v[110:113], v100 offset:1296
	ds_read_b128 v[114:117], v100 offset:1344
	ds_read_b128 v[118:121], v100 offset:1360
	ds_read_b128 v[122:125], v100 offset:1408
	ds_read_b128 v[126:129], v100 offset:1424
	ds_read_b128 v[130:133], v100 offset:1472
	ds_read_b128 v[134:137], v100 offset:1488
	v_pk_add_f32 v[90:91], v[90:91], v[92:93]
	s_nop 0
	v_add_f32_e32 v141, v90, v91
	s_waitcnt lgkmcnt(8)
	v_pk_mul_f32 v[86:87], v[22:23], v[54:55]
	v_pk_mul_f32 v[88:89], v[24:25], v[56:57]
	v_pk_fma_f32 v[86:87], v[26:27], v[58:59], v[86:87]
	v_pk_fma_f32 v[88:89], v[28:29], v[60:61], v[88:89]
	v_pk_fma_f32 v[86:87], v[30:31], v[62:63], v[86:87]
	v_pk_fma_f32 v[88:89], v[32:33], v[64:65], v[88:89]
	v_pk_fma_f32 v[86:87], v[34:35], v[66:67], v[86:87]
	v_pk_fma_f32 v[88:89], v[36:37], v[68:69], v[88:89]
	v_pk_fma_f32 v[86:87], v[38:39], v[70:71], v[86:87]
	v_pk_fma_f32 v[88:89], v[40:41], v[72:73], v[88:89]
	v_pk_fma_f32 v[86:87], v[42:43], v[74:75], v[86:87]
	v_pk_fma_f32 v[88:89], v[44:45], v[76:77], v[88:89]
	v_pk_fma_f32 v[86:87], v[46:47], v[78:79], v[86:87]
	v_pk_fma_f32 v[88:89], v[48:49], v[80:81], v[88:89]
	v_pk_fma_f32 v[86:87], v[50:51], v[82:83], v[86:87]
	v_pk_fma_f32 v[88:89], v[52:53], v[84:85], v[88:89]
	ds_read_b128 v[54:57], v100 offset:1536
	ds_read_b128 v[58:61], v100 offset:1552
	ds_read_b128 v[62:65], v100 offset:1600
	ds_read_b128 v[66:69], v100 offset:1616
	ds_read_b128 v[70:73], v100 offset:1664
	ds_read_b128 v[74:77], v100 offset:1680
	ds_read_b128 v[78:81], v100 offset:1728
	ds_read_b128 v[82:85], v100 offset:1744
	v_pk_add_f32 v[86:87], v[86:87], v[88:89]
	s_nop 0
	v_add_f32_e32 v142, v86, v87
	s_waitcnt lgkmcnt(8)
	v_pk_mul_f32 v[90:91], v[22:23], v[106:107]
	v_pk_mul_f32 v[92:93], v[24:25], v[108:109]
	v_pk_fma_f32 v[90:91], v[26:27], v[110:111], v[90:91]
	v_pk_fma_f32 v[92:93], v[28:29], v[112:113], v[92:93]
	v_pk_fma_f32 v[90:91], v[30:31], v[114:115], v[90:91]
	v_pk_fma_f32 v[92:93], v[32:33], v[116:117], v[92:93]
	v_pk_fma_f32 v[90:91], v[34:35], v[118:119], v[90:91]
	v_pk_fma_f32 v[92:93], v[36:37], v[120:121], v[92:93]
	v_pk_fma_f32 v[90:91], v[38:39], v[122:123], v[90:91]
	v_pk_fma_f32 v[92:93], v[40:41], v[124:125], v[92:93]
	v_pk_fma_f32 v[90:91], v[42:43], v[126:127], v[90:91]
	v_pk_fma_f32 v[92:93], v[44:45], v[128:129], v[92:93]
	v_pk_fma_f32 v[90:91], v[46:47], v[130:131], v[90:91]
	v_pk_fma_f32 v[92:93], v[48:49], v[132:133], v[92:93]
	v_pk_fma_f32 v[90:91], v[50:51], v[134:135], v[90:91]
	v_pk_fma_f32 v[92:93], v[52:53], v[136:137], v[92:93]
	s_nop 0
	v_pk_add_f32 v[90:91], v[90:91], v[92:93]
	s_nop 0
	v_add_f32_e32 v143, v90, v91
	s_waitcnt lgkmcnt(0)
; #define SBAR() __builtin_amdgcn_sched_barrier(0)
; __device__ __forceinline__ unsigned moba_select(int b, int h, int qb, const f16_t* Q, const float* __restrict__ kms) {
;     ...
;     for (int j = 0; j < 7; ++j) {
;         float s = 0.f;
;         if (j < qb) {
;             const float* km = kms + (size_t)(b * NBLK + j) * AW + h * HD + hi * 8;
; #pragma unroll
;             for (int d0 = 0; d0 < 4; ++d0) {
;                 const f32x4 k0 = *(const f32x4*)(km + d0 * 16), k1 = *(const f32x4*)(km + d0 * 16 + 4);
;                 s += (float)qr[d0][0] * k0[0] + (float)qr[d0][1] * k0[1] + (float)qr[d0][2] * k0[2] + (float)qr[d0][3] * k0[3];
;                 s += (float)qr[d0][4] * k1[0] + (float)qr[d0][5] * k1[1] + (float)qr[d0][6] * k1[2] + (float)qr[d0][7] * k1[3];
;             }
;             s += __shfl_xor(s, 32);
;         } else s = -INFINITY;
;         gsc[j] = s;
;     }
;     unsigned sm = 0u;
; #pragma unroll
;     for (int j = 0; j < 7; ++j) {
;         int cnt = 0;
; #pragma unroll
;         for (int i = 0; i < 7; ++i) { if (i == j) continue; const bool ahead = (gsc[i] > gsc[j]) || (gsc[i] == gsc[j] && i < j); cnt += ahead ? 1 : 0; }
;         if (j < qb && cnt < 3) sm |= (1u << j);
;     }
;     return sm;
; template <int THRL> __device__ __forceinline__ void attn_unit(int b, int h, int qb, const f16_t* Q, const f16_t* __restrict__ K, const f16_t* __restrict__ V, f16_t* O, const float* __restrict__ kms, char* shm) {
;     ...
;     if (maskon) selmask = moba_select(b, h, qb, Q, kms);
;     asm volatile("" : "+v"(selmask) :: "memory"); SBAR();
;     f16x8 qr[4];
; #pragma unroll
;     for (int d0 = 0; d0 < 4; ++d0) qr[d0] = *reinterpret_cast<const f16x8*>(&Qw[(long)r32 * QP + d0 * 16 + hi * 8]);
	v_pk_mul_f32 v[86:87], v[22:23], v[54:55]
	v_pk_mul_f32 v[88:89], v[24:25], v[56:57]
	v_pk_fma_f32 v[86:87], v[26:27], v[58:59], v[86:87]
	v_pk_fma_f32 v[88:89], v[28:29], v[60:61], v[88:89]
	v_pk_fma_f32 v[86:87], v[30:31], v[62:63], v[86:87]
	v_pk_fma_f32 v[88:89], v[32:33], v[64:65], v[88:89]
	v_pk_fma_f32 v[86:87], v[34:35], v[66:67], v[86:87]
	v_pk_fma_f32 v[88:89], v[36:37], v[68:69], v[88:89]
	v_pk_fma_f32 v[86:87], v[38:39], v[70:71], v[86:87]
	v_pk_fma_f32 v[88:89], v[40:41], v[72:73], v[88:89]
	v_pk_fma_f32 v[86:87], v[42:43], v[74:75], v[86:87]
	v_pk_fma_f32 v[88:89], v[44:45], v[76:77], v[88:89]
	v_pk_fma_f32 v[86:87], v[46:47], v[78:79], v[86:87]
	v_pk_fma_f32 v[88:89], v[48:49], v[80:81], v[88:89]
	v_pk_fma_f32 v[86:87], v[50:51], v[82:83], v[86:87]
	v_pk_fma_f32 v[88:89], v[52:53], v[84:85], v[88:89]
	s_nop 0
	v_pk_add_f32 v[86:87], v[86:87], v[88:89]
	s_nop 0
	v_add_f32_e32 v144, v86, v87
	v_mov_b32_e32 v54, v138
	v_mov_b32_e32 v55, v139
	v_mov_b32_e32 v56, v140
	v_mov_b32_e32 v57, v141
	v_mov_b32_e32 v58, v142
	v_mov_b32_e32 v59, v143
	v_mov_b32_e32 v60, v144
	s_nop 1
	v_permlane32_swap_b32_e32 v138, v54
	v_permlane32_swap_b32_e32 v139, v55
	v_permlane32_swap_b32_e32 v140, v56
	v_permlane32_swap_b32_e32 v141, v57
	v_permlane32_swap_b32_e32 v142, v58
	v_permlane32_swap_b32_e32 v143, v59
	v_permlane32_swap_b32_e32 v144, v60
	v_add_f32_e32 v138, v138, v54
	v_add_f32_e32 v139, v139, v55
	v_add_f32_e32 v140, v140, v56
	v_add_f32_e32 v141, v141, v57
	v_add_f32_e32 v142, v142, v58
	v_add_f32_e32 v143, v143, v59
	v_add_f32_e32 v144, v144, v60
	v_mov_b32_e32 v146, 0xff800000
	s_cmp_gt_u32 s70, 4
	s_cselect_b64 s[30:31], -1, 0
	v_cndmask_b32_e64 v142, v146, v142, s[30:31]
	s_cmp_gt_u32 s70, 5
	s_cselect_b64 s[30:31], -1, 0
	v_cndmask_b32_e64 v143, v146, v143, s[30:31]
	s_cmp_gt_u32 s70, 6
	s_cselect_b64 s[30:31], -1, 0
	v_cndmask_b32_e64 v144, v146, v144, s[30:31]
	v_mov_b32_e32 v151, 6
	v_mov_b32_e32 v152, 5
	v_mov_b32_e32 v153, 4
	v_mov_b32_e32 v154, 3
	v_mov_b32_e32 v155, 2
	v_mov_b32_e32 v156, 1
	v_mov_b32_e32 v157, 0
	v_cmp_ge_f32_e64 s[0:1], v138, v139
	v_cmp_ge_f32_e64 s[30:31], v138, v140
	v_cmp_ge_f32_e64 s[36:37], v138, v141
	v_addc_co_u32_e64 v152, vcc, 0, v152, s[0:1]
	v_subb_co_u32_e64 v151, vcc, v151, 0, s[0:1]
	v_cmp_ge_f32_e64 s[98:99], v138, v142
	v_addc_co_u32_e64 v153, vcc, 0, v153, s[30:31]
	v_subb_co_u32_e64 v151, vcc, v151, 0, s[30:31]
	v_cmp_ge_f32_e64 s[0:1], v138, v143
	v_addc_co_u32_e64 v154, vcc, 0, v154, s[36:37]
	v_subb_co_u32_e64 v151, vcc, v151, 0, s[36:37]
	v_cmp_ge_f32_e64 s[30:31], v138, v144
	v_addc_co_u32_e64 v155, vcc, 0, v155, s[98:99]
	v_subb_co_u32_e64 v151, vcc, v151, 0, s[98:99]
	v_cmp_ge_f32_e64 s[36:37], v139, v140
	v_addc_co_u32_e64 v156, vcc, 0, v156, s[0:1]
	v_subb_co_u32_e64 v151, vcc, v151, 0, s[0:1]
	v_cmp_ge_f32_e64 s[98:99], v139, v141
	v_addc_co_u32_e64 v157, vcc, 0, v157, s[30:31]
	v_subb_co_u32_e64 v151, vcc, v151, 0, s[30:31]
	v_cmp_ge_f32_e64 s[0:1], v139, v142
	v_addc_co_u32_e64 v153, vcc, 0, v153, s[36:37]
	v_subb_co_u32_e64 v152, vcc, v152, 0, s[36:37]
	v_cmp_ge_f32_e64 s[30:31], v139, v143
	v_addc_co_u32_e64 v154, vcc, 0, v154, s[98:99]
	v_subb_co_u32_e64 v152, vcc, v152, 0, s[98:99]
	v_cmp_ge_f32_e64 s[36:37], v139, v144
	v_addc_co_u32_e64 v155, vcc, 0, v155, s[0:1]
	v_subb_co_u32_e64 v152, vcc, v152, 0, s[0:1]
	v_cmp_ge_f32_e64 s[98:99], v140, v141
	v_addc_co_u32_e64 v156, vcc, 0, v156, s[30:31]
	v_subb_co_u32_e64 v152, vcc, v152, 0, s[30:31]
	v_cmp_ge_f32_e64 s[0:1], v140, v142
	v_addc_co_u32_e64 v157, vcc, 0, v157, s[36:37]
	v_subb_co_u32_e64 v152, vcc, v152, 0, s[36:37]
	v_cmp_ge_f32_e64 s[30:31], v140, v143
	v_addc_co_u32_e64 v154, vcc, 0, v154, s[98:99]
	v_subb_co_u32_e64 v153, vcc, v153, 0, s[98:99]
	v_cmp_ge_f32_e64 s[36:37], v140, v144
	v_addc_co_u32_e64 v155, vcc, 0, v155, s[0:1]
	v_subb_co_u32_e64 v153, vcc, v153, 0, s[0:1]
	v_cmp_ge_f32_e64 s[98:99], v141, v142
	v_addc_co_u32_e64 v156, vcc, 0, v156, s[30:31]
	v_subb_co_u32_e64 v153, vcc, v153, 0, s[30:31]
	v_cmp_ge_f32_e64 s[0:1], v141, v143
	v_addc_co_u32_e64 v157, vcc, 0, v157, s[36:37]
	v_subb_co_u32_e64 v153, vcc, v153, 0, s[36:37]
	v_cmp_ge_f32_e64 s[30:31], v141, v144
	v_addc_co_u32_e64 v155, vcc, 0, v155, s[98:99]
	v_subb_co_u32_e64 v154, vcc, v154, 0, s[98:99]
	v_cmp_ge_f32_e64 s[36:37], v142, v143
	v_addc_co_u32_e64 v156, vcc, 0, v156, s[0:1]
	v_subb_co_u32_e64 v154, vcc, v154, 0, s[0:1]
	v_cmp_ge_f32_e64 s[98:99], v142, v144
	v_addc_co_u32_e64 v157, vcc, 0, v157, s[30:31]
	v_subb_co_u32_e64 v154, vcc, v154, 0, s[30:31]
	v_cmp_ge_f32_e64 s[0:1], v143, v144
	v_addc_co_u32_e64 v156, vcc, 0, v156, s[36:37]
	v_subb_co_u32_e64 v155, vcc, v155, 0, s[36:37]
	s_nop 0
	v_addc_co_u32_e64 v157, vcc, 0, v157, s[98:99]
	v_subb_co_u32_e64 v155, vcc, v155, 0, s[98:99]
	s_nop 0
	v_addc_co_u32_e64 v157, vcc, 0, v157, s[0:1]
	v_subb_co_u32_e64 v156, vcc, v156, 0, s[0:1]
	s_nop 1
	v_cmp_gt_u32_e64 s[0:1], 3, v151
	v_cmp_gt_u32_e64 s[30:31], 3, v152
	v_cmp_gt_u32_e64 s[36:37], 3, v153
	v_cndmask_b32_e64 v147, 0, 1, s[0:1]
	v_cmp_gt_u32_e64 s[98:99], 3, v154
	v_cndmask_b32_e64 v148, 0, 2, s[30:31]
	v_cmp_gt_u32_e64 s[0:1], 3, v155
	v_cndmask_b32_e64 v149, 0, 4, s[36:37]
	v_cmp_gt_u32_e64 s[30:31], 3, v156
	v_cndmask_b32_e64 v158, 0, 8, s[98:99]
	v_cmp_gt_u32_e64 s[36:37], 3, v157
	v_cndmask_b32_e64 v159, 0, 16, s[0:1]
	s_nop 0
	v_cndmask_b32_e64 v160, 0, 32, s[30:31]
	v_cndmask_b32_e64 v161, 0, 64, s[36:37]
	s_lshl_b32 s9, 1, s70
	s_add_i32 s9, s9, -1
	v_or3_b32 v210, v147, v148, v149
	v_or3_b32 v210, v210, v158, v159
	v_or3_b32 v210, v210, v160, v161
	v_and_b32_e32 v210, s9, v210
	v_mov_b64_e32 v[138:139], v[2:3]
	v_mov_b64_e32 v[140:141], v[4:5]
	v_mov_b64_e32 v[130:131], v[6:7]
	v_mov_b64_e32 v[132:133], v[8:9]
	v_mov_b64_e32 v[118:119], v[10:11]
	v_mov_b64_e32 v[120:121], v[12:13]
	v_mov_b64_e32 v[114:115], v[14:15]
	v_mov_b64_e32 v[116:117], v[16:17]
; #define WAIT_BAR(N) asm volatile("s_waitcnt vmcnt(" #N ") lgkmcnt(0)\n\ts_barrier" ::: "memory")
; #define DMA_K(t, slot) glds16(ksrc + (long)(t) * KVBLK * KP, (unsigned)__builtin_amdgcn_readfirstlane(kdst + (slot)))
; #define CMASK(P0, P1, t) do { int jb_ = (t) - (NT - 4); if (jb_ >= 0 && 64 * jb_ + 63 > wid * QBLK) { int q_ = r32; asm volatile("" : "+v"(q_)); cmask(P0, P1, jb_, wid * QBLK + q_, hi); } } while (0)
; template <int THRL> __device__ __forceinline__ void attn_unit(int b, int h, int qb, const f16_t* Q, const f16_t* __restrict__ K, const f16_t* __restrict__ V, f16_t* O, const float* __restrict__ kms, char* shm) {
;     ...
;     f16x8 qr[4];
; #pragma unroll
;     for (int d0 = 0; d0 < 4; ++d0) qr[d0] = *reinterpret_cast<const f16x8*>(&Qw[(long)r32 * QP + d0 * 16 + hi * 8]);
;     float mhat = 0.f, l_reg = 0.f; float z_; asm volatile("v_mov_b32 %0, 0" : "=v"(z_)); f32x16 o[2]; f32x16 negm;
;     ...
;     _Pragma("unroll") for (int r = 0; r < 16; ++r) { o[0][r] = z_; o[1][r] = z_; negm[r] = KEEP(0) ? z_ : -INFINITY; } asm volatile("" : "+v"(negm));
;     ...
;     bool resc = false;
;     ...
;     f32x16 pA0, pA1, pB0, pB1;
;     int sl_prev = 0, sl_cur = 0, sl_next = SLOTB;
;     ...
;     DMA_K(2, 2 * SLOTB);
;     WAIT_BAR(3);
;     qkt(pA0, pA1, Kbase, qr, negm, r32, hi); asm volatile("s_nop 15\n\ts_nop 7" : "+v"(pA0), "+v"(pA1)); CMASK(pA0, pA1, 0);
.LBB0_538:
	s_lshl_b32 s89, s29, 5
	s_xor_b64 s[0:1], s[2:3], -1
	s_ashr_i32 s2, s89, 31
	s_add_u32 s36, s8, s89
	s_addc_u32 s37, s57, s2
	v_and_b32_e32 v190, 31, v150
	v_lshrrev_b32_e32 v204, 5, v201
	s_lshl_b64 s[2:3], s[36:37], 11
	s_add_u32 s2, s79, s2
	v_lshlrev_b32_e32 v2, 10, v204
	v_lshlrev_b32_e32 v3, 4, v190
	s_addc_u32 s3, s14, s3
	v_add3_u32 v211, 0, v2, v3
	v_lshlrev_b32_e32 v2, 11, v190
	v_lshl_or_b32 v2, v204, 4, v2
	s_waitcnt lgkmcnt(10)
	s_and_b64 vcc, exec, s[4:5]
	s_cbranch_vccnz .Lattn_q_loaded
	global_load_dwordx4 v[138:141], v2, s[2:3]
	global_load_dwordx4 v[130:133], v2, s[2:3] offset:32
	global_load_dwordx4 v[118:121], v2, s[2:3] offset:64
	global_load_dwordx4 v[114:117], v2, s[2:3] offset:96
.Lattn_q_loaded:
	v_and_b32_e32 v3, 1, v210
	v_cmp_eq_u32_e32 vcc, 0, v3
	s_and_b64 s[2:3], s[4:5], vcc
	s_cmp_lg_u32 0, -1
	v_mov_b32 v2, 0
	s_cselect_b32 s8, 0, 0
	v_cndmask_b32_e64 v18, v2, v200, s[2:3]
	v_mov_b32_e32 v19, v18
	v_mov_b32_e32 v20, v18
	v_mov_b32_e32 v21, v18
	v_mov_b32_e32 v22, v18
	v_mov_b32_e32 v23, v18
	v_mov_b32_e32 v24, v18
	v_mov_b32_e32 v25, v18
	v_mov_b32_e32 v26, v18
	v_mov_b32_e32 v27, v18
	v_mov_b32_e32 v28, v18
	v_mov_b32_e32 v29, v18
	v_mov_b32_e32 v30, v18
	v_mov_b32_e32 v31, v18
	v_mov_b32_e32 v32, v18
	v_mov_b32_e32 v33, v18
	s_waitcnt vmcnt(3) lgkmcnt(0)
	s_barrier
	s_waitcnt vmcnt(5)
	ds_read_b128 v[4:7], v211
	s_cmp_lg_u32 s70, 0
	s_cselect_b64 s[8:9], -1, 0
	s_cmp_eq_u32 s70, 0
	s_cselect_b64 s[30:31], -1, 0
	s_cmp_lt_i32 s29, 2
	s_cselect_b64 s[52:53], -1, 0
	s_and_b64 s[30:31], s[30:31], s[52:53]
	s_andn2_b64 vcc, exec, s[30:31]
	v_lshlrev_b32_e32 v208, 2, v204
	s_waitcnt vmcnt(3) lgkmcnt(0)
	v_mfma_f32_32x32x16_f16 v[34:49], v[4:7], v[138:141], v[18:33]
	ds_read_b128 v[4:7], v211 offset:512
	s_waitcnt lgkmcnt(0)
	v_mfma_f32_32x32x16_f16 v[18:33], v[4:7], v[138:141], v[18:33]
	ds_read_b128 v[4:7], v211 offset:2048
	s_waitcnt vmcnt(2) lgkmcnt(0)
	v_mfma_f32_32x32x16_f16 v[34:49], v[4:7], v[130:133], v[34:49]
	ds_read_b128 v[4:7], v211 offset:2560
	s_waitcnt lgkmcnt(0)
	v_mfma_f32_32x32x16_f16 v[18:33], v[4:7], v[130:133], v[18:33]
	ds_read_b128 v[4:7], v211 offset:4096
	s_waitcnt vmcnt(1) lgkmcnt(0)
	v_mfma_f32_32x32x16_f16 v[34:49], v[4:7], v[118:121], v[34:49]
	ds_read_b128 v[4:7], v211 offset:4608
	s_waitcnt lgkmcnt(0)
	v_mfma_f32_32x32x16_f16 v[18:33], v[4:7], v[118:121], v[18:33]
	ds_read_b128 v[4:7], v211 offset:6144
	s_waitcnt vmcnt(0) lgkmcnt(0)
	v_mfma_f32_32x32x16_f16 v[34:49], v[4:7], v[114:117], v[34:49]
	ds_read_b128 v[4:7], v211 offset:6656
	s_waitcnt lgkmcnt(0)
	v_mfma_f32_32x32x16_f16 v[18:33], v[4:7], v[114:117], v[18:33]
	s_nop 15
	s_nop 7
	s_cbranch_vccnz .LBB0_540
	v_mov_b32_e32 v3, v190
	v_or_b32_e32 v4, 32, v208
	v_add_u32_e32 v3, s89, v3
	v_cmp_le_i32_e32 vcc, v4, v3
	v_or_b32_e32 v4, 33, v208
	s_nop 5
	v_cndmask_b32_e32 v18, v200, v18, vcc
	v_cmp_lt_i32_e32 vcc, v208, v3
	s_nop 1
	v_cndmask_b32_e32 v35, v200, v35, vcc
	v_cmp_le_i32_e32 vcc, v208, v3
	s_nop 1
	v_cndmask_b32_e32 v34, v200, v34, vcc
	v_cmp_le_i32_e32 vcc, v4, v3
	v_or_b32_e32 v4, 2, v208
	s_nop 0
	v_cndmask_b32_e32 v19, v200, v19, vcc
	v_cmp_le_i32_e32 vcc, v4, v3
	v_or_b32_e32 v4, 34, v208
	s_nop 0
	v_cndmask_b32_e32 v36, v200, v36, vcc
	v_cmp_le_i32_e32 vcc, v4, v3
	v_or_b32_e32 v4, 3, v208
	s_nop 0
	v_cndmask_b32_e32 v20, v200, v20, vcc
	v_cmp_le_i32_e32 vcc, v4, v3
	v_or_b32_e32 v4, 35, v208
	s_nop 0
	v_cndmask_b32_e32 v37, v200, v37, vcc
	v_cmp_le_i32_e32 vcc, v4, v3
	v_or_b32_e32 v4, 8, v208
	s_nop 0
	v_cndmask_b32_e32 v21, v200, v21, vcc
	v_cmp_le_i32_e32 vcc, v4, v3
	v_or_b32_e32 v4, 40, v208
	s_nop 0
	v_cndmask_b32_e32 v38, v200, v38, vcc
	v_cmp_le_i32_e32 vcc, v4, v3
	v_or_b32_e32 v4, 9, v208
	s_nop 0
	v_cndmask_b32_e32 v22, v200, v22, vcc
	v_cmp_le_i32_e32 vcc, v4, v3
	v_or_b32_e32 v4, 41, v208
	s_nop 0
	v_cndmask_b32_e32 v39, v200, v39, vcc
	v_cmp_le_i32_e32 vcc, v4, v3
	v_or_b32_e32 v4, 10, v208
	s_nop 0
	v_cndmask_b32_e32 v23, v200, v23, vcc
	v_cmp_le_i32_e32 vcc, v4, v3
	v_or_b32_e32 v4, 42, v208
	s_nop 0
	v_cndmask_b32_e32 v40, v200, v40, vcc
	v_cmp_le_i32_e32 vcc, v4, v3
	v_or_b32_e32 v4, 11, v208
	s_nop 0
	v_cndmask_b32_e32 v24, v200, v24, vcc
	v_cmp_le_i32_e32 vcc, v4, v3
	v_or_b32_e32 v4, 43, v208
	s_nop 0
	v_cndmask_b32_e32 v41, v200, v41, vcc
	v_cmp_le_i32_e32 vcc, v4, v3
	v_or_b32_e32 v4, 16, v208
	s_nop 0
	v_cndmask_b32_e32 v25, v200, v25, vcc
	v_cmp_le_i32_e32 vcc, v4, v3
	v_or_b32_e32 v4, 48, v208
	s_nop 0
	v_cndmask_b32_e32 v42, v200, v42, vcc
	v_cmp_le_i32_e32 vcc, v4, v3
	v_or_b32_e32 v4, 17, v208
	s_nop 0
	v_cndmask_b32_e32 v26, v200, v26, vcc
	v_cmp_le_i32_e32 vcc, v4, v3
	v_or_b32_e32 v4, 49, v208
	s_nop 0
	v_cndmask_b32_e32 v43, v200, v43, vcc
	v_cmp_le_i32_e32 vcc, v4, v3
	v_or_b32_e32 v4, 18, v208
	s_nop 0
	v_cndmask_b32_e32 v27, v200, v27, vcc
	v_cmp_le_i32_e32 vcc, v4, v3
	v_or_b32_e32 v4, 50, v208
	s_nop 0
	v_cndmask_b32_e32 v44, v200, v44, vcc
	v_cmp_le_i32_e32 vcc, v4, v3
	v_or_b32_e32 v4, 19, v208
	s_nop 0
	v_cndmask_b32_e32 v28, v200, v28, vcc
	v_cmp_le_i32_e32 vcc, v4, v3
	v_or_b32_e32 v4, 51, v208
	s_nop 0
	v_cndmask_b32_e32 v45, v200, v45, vcc
	v_cmp_le_i32_e32 vcc, v4, v3
	v_or_b32_e32 v4, 24, v208
	s_nop 0
	v_cndmask_b32_e32 v29, v200, v29, vcc
	v_cmp_le_i32_e32 vcc, v4, v3
	v_or_b32_e32 v4, 56, v208
	s_nop 0
	v_cndmask_b32_e32 v46, v200, v46, vcc
	v_cmp_le_i32_e32 vcc, v4, v3
	v_or_b32_e32 v4, 25, v208
	s_nop 0
	v_cndmask_b32_e32 v30, v200, v30, vcc
	v_cmp_le_i32_e32 vcc, v4, v3
	v_or_b32_e32 v4, 57, v208
	s_nop 0
	v_cndmask_b32_e32 v47, v200, v47, vcc
	v_cmp_le_i32_e32 vcc, v4, v3
	v_or_b32_e32 v4, 26, v208
	s_nop 0
	v_cndmask_b32_e32 v31, v200, v31, vcc
	v_cmp_le_i32_e32 vcc, v4, v3
	v_or_b32_e32 v4, 58, v208
	s_nop 0
	v_cndmask_b32_e32 v48, v200, v48, vcc
	v_cmp_le_i32_e32 vcc, v4, v3
	v_or_b32_e32 v4, 27, v208
	s_nop 0
	v_cndmask_b32_e32 v32, v200, v32, vcc
	v_cmp_le_i32_e32 vcc, v4, v3
	v_or_b32_e32 v4, 59, v208
	s_nop 0
	v_cndmask_b32_e32 v49, v200, v49, vcc
	v_cmp_le_i32_e32 vcc, v4, v3
	s_nop 1
	v_cndmask_b32_e32 v33, v200, v33, vcc
